# combine loop batched (4 rows, 9 loads each in flight) + prologue transpose readback with all 32 ds_read2 in flight + pool tasks rewritten as one compact generic body with kc loop
# speedup vs baseline: 1.0016x; 1.0016x over previous
; template <int W> __device__ __forceinline__ void pool_task(const bf16* __restrict__ z, const bf16* __restrict__ pwt, const float* __restrict__ pool_scale, bf16* __restrict__ y, int g, int r0, int lane) {
;     const int fr = lane & 15, fq = lane >> 4, row = r0 + fr, pos = row & (SEQ - 1);
;     const int cnt = (pos + 1) < W ? (pos + 1) : W; const float icnt = 1.0f / (float)cnt;
;     constexpr int CH = W < 8 ? W : 8;
;     bf16x8 af[4];
; #pragma unroll
;     for (int kc = 0; kc < 4; ++kc) { const bf16* zp = z + (size_t)row * DIN + 4608 + 128 * g + 32 * kc + 8 * fq;
;         const v4u u0 = *(const v4u*)zp;
;         float sm[8];
; #pragma unroll
;         for (int i = 0; i < 8; ++i) sm[i] = 0.f;
; #pragma unroll
;         for (int c0 = 0; c0 < W; c0 += CH) {
;             v4u u[CH];
; #pragma unroll
;             for (int j = 0; j < CH; ++j) { const int lag = c0 + j, lg = lag < cnt ? lag : 0; u[j] = *(const v4u*)(zp - (size_t)lg * DIN); }
; #pragma unroll
;             for (int j = 0; j < CH; ++j) { const float wgt = (c0 + j) < cnt ? 1.0f : 0.0f;
; #pragma unroll
;                 for (int i = 0; i < 4; ++i) { sm[2 * i] += wgt * bflo(u[j][i]); sm[2 * i + 1] += wgt * bfhi(u[j][i]); } }
;             asm volatile("" ::: "memory");
;         }
;         v4u pw;
; #pragma unroll
;         for (int i = 0; i < 4; ++i) pw[i] = pk2(sm[2 * i] * icnt - bflo(u0[i]), sm[2 * i + 1] * icnt - bfhi(u0[i]));
;         af[kc] = __builtin_bit_cast(bf16x8, pw); }
;     const bf16* wg = pwt + (size_t)g * 16384 + (size_t)fr * 128 + 8 * fq;
; #pragma unroll 1
;     for (int nh = 0; nh < 2; ++nh) {
;         bf16x8 wf[4][4]; f32x4 sc[4];
; #pragma unroll
;         for (int q = 0; q < 4; ++q) { const int nt = 4 * nh + q;
; #pragma unroll
;             for (int kc = 0; kc < 4; ++kc) wf[q][kc] = *(const bf16x8*)(wg + (size_t)nt * 16 * 128 + 32 * kc);
;             sc[q] = *(const f32x4*)(pool_scale + 128 * g + 16 * nt + 4 * fq); }
; __device__ __forceinline__ void misc_phase(const bf16* __restrict__ z, const bf16* __restrict__ op, const float* __restrict__ lse, const float* __restrict__ conv_w, const bf16* __restrict__ pwt, const float* __restrict__ pool_scale, bf16* __restrict__ y, int gw, int NGW, int lane) {
;     ...
;     for (int t = gw; t < 4 * (M / 16); t += NGW) {
;         const int g = (t & 3) ^ (((t >> 11) & 1) * 3), r0 = (t >> 2) * 16;
.LBB0_394:
	s_bfe_u32 s0, s16, 0x1000b
	s_mul_i32 s0, s0, 3
	s_and_b32 s1, s16, 3
	s_xor_b32 s14, s0, s1
	s_lshl_b32 s3, s16, 2
	s_and_b32 s3, s3, -16
	s_lshl_b32 s15, 2, s14
	s_sub_u32 s15, s15, 1
	s_lshl_b32 s12, s14, 8
	s_add_u32 s12, s12, 0x2400
	s_mov_b64 s[0:1], s[48:49]
	v_readlane_b32 s4, v254, 41
	v_readlane_b32 s5, v254, 42
	s_lshl_b32 s6, s22, 17
	s_lshl_b32 s7, s14, 15
	s_add_u32 s6, s6, s7
	s_add_u32 s6, s4, s6
	s_addc_u32 s7, s5, 0
	s_lshl_b32 s8, s22, 11
	s_lshl_b32 s9, s14, 9
	s_add_u32 s9, s8, s9
	s_add_u32 s8, s78, s9
	s_addc_u32 s9, s79, 0
	s_lshl_b32 s10, s14, 8
	s_add_u32 s10, s10, 0xc00
	s_add_u32 s10, s54, s10
	s_addc_u32 s11, s55, 0
	v_and_b32_e32 v247, 15, v48
	v_lshrrev_b32_e32 v248, 4, v48
	v_or_b32_e32 v249, s3, v247
	v_and_b32_e32 v246, 0x1fff, v249
	v_min_u32_e32 v246, s15, v246
	v_mul_u32_u24_e32 v203, 0x2800, v249
	v_lshl_add_u32 v203, v248, 4, v203
	v_add_u32_e32 v203, s12, v203
	v_lshlrev_b32_e32 v243, 12, v249
	v_lshl_add_u32 v243, v248, 3, v243
	v_lshlrev_b32_e32 v235, 8, v247
	v_lshl_add_u32 v235, v248, 4, v235
	v_add_u32_e32 v236, 0x1000, v235
	v_add_u32_e32 v237, 0x2000, v235
	v_add_u32_e32 v238, 0x3000, v235
	v_add_u32_e32 v239, 0x4000, v235
	v_add_u32_e32 v240, 0x5000, v235
	v_add_u32_e32 v241, 0x6000, v235
	v_add_u32_e32 v242, 0x7000, v235
	v_lshlrev_b32_e32 v244, 4, v248
	v_add_u32_e32 v250, 1, v246
	v_cvt_f32_ubyte0_e32 v250, v250
	v_div_scale_f32 v247, vcc, v250, v250, 1.0
	v_rcp_f32_e32 v248, v247
	s_nop 0
	v_fma_f32 v249, -v247, v248, 1.0
	v_fmac_f32_e32 v248, v249, v248
	v_div_scale_f32 v219, vcc, 1.0, v250, 1.0
	v_mul_f32_e32 v220, v219, v248
	v_fma_f32 v221, -v247, v220, v219
	v_fmac_f32_e32 v220, v221, v248
	v_fma_f32 v247, -v247, v220, v219
	v_div_fmas_f32 v247, v247, v248, v220
	v_div_fixup_f32 v245, v247, v250, 1.0
	v_cmp_le_u32_e32 vcc, 1, v246
	v_mov_b32_e32 v204, 0x2800
	s_nop 0
	v_cndmask_b32_e64 v188, 0, 1.0, vcc
	v_cndmask_b32_e32 v204, 0, v204, vcc
	v_sub_u32_e32 v204, v203, v204
	v_cmp_le_u32_e32 vcc, 2, v246
	v_mov_b32_e32 v205, 0x5000
	s_nop 0
	v_cndmask_b32_e64 v189, 0, 1.0, vcc
	v_cndmask_b32_e32 v205, 0, v205, vcc
	v_sub_u32_e32 v205, v203, v205
	v_cmp_le_u32_e32 vcc, 3, v246
	v_mov_b32_e32 v206, 0x7800
	s_nop 0
	v_cndmask_b32_e64 v190, 0, 1.0, vcc
	v_cndmask_b32_e32 v206, 0, v206, vcc
	v_sub_u32_e32 v206, v203, v206
	v_cmp_le_u32_e32 vcc, 4, v246
	v_mov_b32_e32 v207, 0xa000
	s_nop 0
	v_cndmask_b32_e64 v191, 0, 1.0, vcc
	v_cndmask_b32_e32 v207, 0, v207, vcc
	v_sub_u32_e32 v207, v203, v207
	v_cmp_le_u32_e32 vcc, 5, v246
	v_mov_b32_e32 v208, 0xc800
	s_nop 0
	v_cndmask_b32_e64 v192, 0, 1.0, vcc
	v_cndmask_b32_e32 v208, 0, v208, vcc
	v_sub_u32_e32 v208, v203, v208
	v_cmp_le_u32_e32 vcc, 6, v246
	v_mov_b32_e32 v209, 0xf000
	s_nop 0
	v_cndmask_b32_e64 v193, 0, 1.0, vcc
	v_cndmask_b32_e32 v209, 0, v209, vcc
	v_sub_u32_e32 v209, v203, v209
	v_cmp_le_u32_e32 vcc, 7, v246
	v_mov_b32_e32 v210, 0x11800
	s_nop 0
	v_cndmask_b32_e64 v194, 0, 1.0, vcc
	v_cndmask_b32_e32 v210, 0, v210, vcc
	v_sub_u32_e32 v210, v203, v210
	v_cmp_le_u32_e32 vcc, 8, v246
	v_mov_b32_e32 v211, 0x14000
	s_nop 0
	v_cndmask_b32_e64 v195, 0, 1.0, vcc
	v_cndmask_b32_e32 v211, 0, v211, vcc
	v_sub_u32_e32 v211, v203, v211
	v_cmp_le_u32_e32 vcc, 9, v246
	v_mov_b32_e32 v212, 0x16800
	s_nop 0
	v_cndmask_b32_e64 v196, 0, 1.0, vcc
	v_cndmask_b32_e32 v212, 0, v212, vcc
	v_sub_u32_e32 v212, v203, v212
	v_cmp_le_u32_e32 vcc, 10, v246
	v_mov_b32_e32 v213, 0x19000
	s_nop 0
	v_cndmask_b32_e64 v197, 0, 1.0, vcc
	v_cndmask_b32_e32 v213, 0, v213, vcc
	v_sub_u32_e32 v213, v203, v213
	v_cmp_le_u32_e32 vcc, 11, v246
	v_mov_b32_e32 v214, 0x1b800
	s_nop 0
	v_cndmask_b32_e64 v198, 0, 1.0, vcc
	v_cndmask_b32_e32 v214, 0, v214, vcc
	v_sub_u32_e32 v214, v203, v214
	v_cmp_le_u32_e32 vcc, 12, v246
	v_mov_b32_e32 v215, 0x1e000
	s_nop 0
	v_cndmask_b32_e64 v199, 0, 1.0, vcc
	v_cndmask_b32_e32 v215, 0, v215, vcc
	v_sub_u32_e32 v215, v203, v215
	v_cmp_le_u32_e32 vcc, 13, v246
	v_mov_b32_e32 v216, 0x20800
	s_nop 0
	v_cndmask_b32_e64 v200, 0, 1.0, vcc
	v_cndmask_b32_e32 v216, 0, v216, vcc
	v_sub_u32_e32 v216, v203, v216
	v_cmp_le_u32_e32 vcc, 14, v246
	v_mov_b32_e32 v217, 0x23000
	s_nop 0
	v_cndmask_b32_e64 v201, 0, 1.0, vcc
	v_cndmask_b32_e32 v217, 0, v217, vcc
	v_sub_u32_e32 v217, v203, v217
	v_cmp_le_u32_e32 vcc, 15, v246
	v_mov_b32_e32 v218, 0x25800
	s_nop 0
	v_cndmask_b32_e64 v202, 0, 1.0, vcc
	v_cndmask_b32_e32 v218, 0, v218, vcc
	v_sub_u32_e32 v218, v203, v218
	v_mov_b32_e32 v102, 0
	v_mov_b32_e32 v103, 0
	v_mov_b32_e32 v104, 0
	v_mov_b32_e32 v105, 0
	v_mov_b32_e32 v106, 0
	v_mov_b32_e32 v107, 0
	v_mov_b32_e32 v108, 0
	v_mov_b32_e32 v109, 0
	v_mov_b32_e32 v110, 0
	v_mov_b32_e32 v111, 0
	v_mov_b32_e32 v112, 0
	v_mov_b32_e32 v113, 0
	v_mov_b32_e32 v114, 0
	v_mov_b32_e32 v115, 0
	v_mov_b32_e32 v116, 0
	v_mov_b32_e32 v117, 0
	v_mov_b32_e32 v118, 0
	v_mov_b32_e32 v119, 0
	v_mov_b32_e32 v120, 0
	v_mov_b32_e32 v121, 0
	v_mov_b32_e32 v122, 0
	v_mov_b32_e32 v123, 0
	v_mov_b32_e32 v124, 0
	v_mov_b32_e32 v125, 0
	v_mov_b32_e32 v126, 0
	v_mov_b32_e32 v127, 0
	v_mov_b32_e32 v128, 0
	v_mov_b32_e32 v129, 0
	v_mov_b32_e32 v130, 0
	v_mov_b32_e32 v131, 0
	v_mov_b32_e32 v132, 0
	v_mov_b32_e32 v133, 0
	s_mov_b32 s13, 0
.Lpl_kc:
	global_load_dwordx4 v[4:7], v203, s[0:1]
	global_load_dwordx4 v[8:11], v204, s[0:1]
	s_cmp_lt_u32 s15, 2
	s_cbranch_scc1 .Lpl_ld_done
	global_load_dwordx4 v[12:15], v205, s[0:1]
	global_load_dwordx4 v[16:19], v206, s[0:1]
	s_cmp_lt_u32 s15, 4
	s_cbranch_scc1 .Lpl_ld_done
	global_load_dwordx4 v[20:23], v207, s[0:1]
	global_load_dwordx4 v[24:27], v208, s[0:1]
	global_load_dwordx4 v[28:31], v209, s[0:1]
	global_load_dwordx4 v[32:35], v210, s[0:1]
	s_cmp_lt_u32 s15, 8
	s_cbranch_scc1 .Lpl_ld_done
	global_load_dwordx4 v[36:39], v211, s[0:1]
	global_load_dwordx4 v[40:43], v212, s[0:1]
	global_load_dwordx4 v[44:47], v213, s[0:1]
	global_load_dwordx4 v[50:53], v214, s[0:1]
	global_load_dwordx4 v[54:57], v215, s[0:1]
	global_load_dwordx4 v[58:61], v216, s[0:1]
	global_load_dwordx4 v[62:65], v217, s[0:1]
	global_load_dwordx4 v[66:69], v218, s[0:1]
; __device__ __forceinline__ float bflo(unsigned w) { return __uint_as_float(w << 16); }
; __device__ __forceinline__ float bfhi(unsigned w) { return __uint_as_float(w & 0xffff0000u); }
; template <int W> __device__ __forceinline__ void pool_task(const bf16* __restrict__ z, const bf16* __restrict__ pwt, const float* __restrict__ pool_scale, bf16* __restrict__ y, int g, int r0, int lane) {
;     ...
;         for (int c0 = 0; c0 < W; c0 += CH) {
;             v4u u[CH];
; #pragma unroll
;             for (int j = 0; j < CH; ++j) { const int lag = c0 + j, lg = lag < cnt ? lag : 0; u[j] = *(const v4u*)(zp - (size_t)lg * DIN); }
; #pragma unroll
;             for (int j = 0; j < CH; ++j) { const float wgt = (c0 + j) < cnt ? 1.0f : 0.0f;
; #pragma unroll
;                 for (int i = 0; i < 4; ++i) { sm[2 * i] += wgt * bflo(u[j][i]); sm[2 * i + 1] += wgt * bfhi(u[j][i]); } }
;     ...
;         for (int q = 0; q < 4; ++q) { const int nt = 4 * nh + q;
; #pragma unroll
;             for (int kc = 0; kc < 4; ++kc) wf[q][kc] = *(const bf16x8*)(wg + (size_t)nt * 16 * 128 + 32 * kc);
.Lpl_ld_done:
	global_load_dwordx4 v[70:73], v235, s[6:7]
	global_load_dwordx4 v[74:77], v236, s[6:7]
	global_load_dwordx4 v[78:81], v237, s[6:7]
	global_load_dwordx4 v[82:85], v238, s[6:7]
	global_load_dwordx4 v[86:89], v239, s[6:7]
	global_load_dwordx4 v[90:93], v240, s[6:7]
	global_load_dwordx4 v[94:97], v241, s[6:7]
	global_load_dwordx4 v[98:101], v242, s[6:7]
	s_waitcnt vmcnt(8)
	v_lshlrev_b32_e32 v219, 16, v4
	v_and_b32_e32 v220, 0xffff0000, v4
	v_lshlrev_b32_e32 v221, 16, v5
	v_and_b32_e32 v222, 0xffff0000, v5
	v_lshlrev_b32_e32 v223, 16, v6
	v_and_b32_e32 v224, 0xffff0000, v6
	v_lshlrev_b32_e32 v225, 16, v7
	v_and_b32_e32 v226, 0xffff0000, v7
	v_add_f32_e32 v227, 0, v219
	v_add_f32_e32 v228, 0, v220
	v_add_f32_e32 v229, 0, v221
	v_add_f32_e32 v230, 0, v222
	v_add_f32_e32 v231, 0, v223
	v_add_f32_e32 v232, 0, v224
	v_add_f32_e32 v233, 0, v225
	v_add_f32_e32 v234, 0, v226
	v_lshlrev_b32_e32 v247, 16, v8
	v_and_b32_e32 v248, 0xffff0000, v8
	v_fmac_f32_e32 v227, v188, v247
	v_fmac_f32_e32 v228, v188, v248
	v_lshlrev_b32_e32 v247, 16, v9
	v_and_b32_e32 v248, 0xffff0000, v9
	v_fmac_f32_e32 v229, v188, v247
	v_fmac_f32_e32 v230, v188, v248
	v_lshlrev_b32_e32 v247, 16, v10
	v_and_b32_e32 v248, 0xffff0000, v10
	v_fmac_f32_e32 v231, v188, v247
	v_fmac_f32_e32 v232, v188, v248
	v_lshlrev_b32_e32 v247, 16, v11
	v_and_b32_e32 v248, 0xffff0000, v11
	v_fmac_f32_e32 v233, v188, v247
	v_fmac_f32_e32 v234, v188, v248
	s_cmp_lt_u32 s15, 2
	s_cbranch_scc1 .Lpl_acc_done
	v_lshlrev_b32_e32 v247, 16, v12
	v_and_b32_e32 v248, 0xffff0000, v12
	v_fmac_f32_e32 v227, v189, v247
	v_fmac_f32_e32 v228, v189, v248
	v_lshlrev_b32_e32 v247, 16, v13
	v_and_b32_e32 v248, 0xffff0000, v13
	v_fmac_f32_e32 v229, v189, v247
	v_fmac_f32_e32 v230, v189, v248
	v_lshlrev_b32_e32 v247, 16, v14
	v_and_b32_e32 v248, 0xffff0000, v14
	v_fmac_f32_e32 v231, v189, v247
	v_fmac_f32_e32 v232, v189, v248
	v_lshlrev_b32_e32 v247, 16, v15
	v_and_b32_e32 v248, 0xffff0000, v15
	v_fmac_f32_e32 v233, v189, v247
	v_fmac_f32_e32 v234, v189, v248
	v_lshlrev_b32_e32 v247, 16, v16
	v_and_b32_e32 v248, 0xffff0000, v16
	v_fmac_f32_e32 v227, v190, v247
	v_fmac_f32_e32 v228, v190, v248
	v_lshlrev_b32_e32 v247, 16, v17
	v_and_b32_e32 v248, 0xffff0000, v17
	v_fmac_f32_e32 v229, v190, v247
	v_fmac_f32_e32 v230, v190, v248
	v_lshlrev_b32_e32 v247, 16, v18
	v_and_b32_e32 v248, 0xffff0000, v18
	v_fmac_f32_e32 v231, v190, v247
	v_fmac_f32_e32 v232, v190, v248
	v_lshlrev_b32_e32 v247, 16, v19
	v_and_b32_e32 v248, 0xffff0000, v19
	v_fmac_f32_e32 v233, v190, v247
	v_fmac_f32_e32 v234, v190, v248
	s_cmp_lt_u32 s15, 4
	s_cbranch_scc1 .Lpl_acc_done
	v_lshlrev_b32_e32 v247, 16, v20
	v_and_b32_e32 v248, 0xffff0000, v20
	v_fmac_f32_e32 v227, v191, v247
	v_fmac_f32_e32 v228, v191, v248
	v_lshlrev_b32_e32 v247, 16, v21
	v_and_b32_e32 v248, 0xffff0000, v21
	v_fmac_f32_e32 v229, v191, v247
	v_fmac_f32_e32 v230, v191, v248
	v_lshlrev_b32_e32 v247, 16, v22
	v_and_b32_e32 v248, 0xffff0000, v22
	v_fmac_f32_e32 v231, v191, v247
	v_fmac_f32_e32 v232, v191, v248
	v_lshlrev_b32_e32 v247, 16, v23
	v_and_b32_e32 v248, 0xffff0000, v23
	v_fmac_f32_e32 v233, v191, v247
	v_fmac_f32_e32 v234, v191, v248
	v_lshlrev_b32_e32 v247, 16, v24
	v_and_b32_e32 v248, 0xffff0000, v24
	v_fmac_f32_e32 v227, v192, v247
	v_fmac_f32_e32 v228, v192, v248
	v_lshlrev_b32_e32 v247, 16, v25
	v_and_b32_e32 v248, 0xffff0000, v25
	v_fmac_f32_e32 v229, v192, v247
	v_fmac_f32_e32 v230, v192, v248
	v_lshlrev_b32_e32 v247, 16, v26
	v_and_b32_e32 v248, 0xffff0000, v26
	v_fmac_f32_e32 v231, v192, v247
	v_fmac_f32_e32 v232, v192, v248
	v_lshlrev_b32_e32 v247, 16, v27
	v_and_b32_e32 v248, 0xffff0000, v27
	v_fmac_f32_e32 v233, v192, v247
	v_fmac_f32_e32 v234, v192, v248
	v_lshlrev_b32_e32 v247, 16, v28
	v_and_b32_e32 v248, 0xffff0000, v28
	v_fmac_f32_e32 v227, v193, v247
	v_fmac_f32_e32 v228, v193, v248
	v_lshlrev_b32_e32 v247, 16, v29
	v_and_b32_e32 v248, 0xffff0000, v29
	v_fmac_f32_e32 v229, v193, v247
	v_fmac_f32_e32 v230, v193, v248
	v_lshlrev_b32_e32 v247, 16, v30
	v_and_b32_e32 v248, 0xffff0000, v30
	v_fmac_f32_e32 v231, v193, v247
	v_fmac_f32_e32 v232, v193, v248
	v_lshlrev_b32_e32 v247, 16, v31
	v_and_b32_e32 v248, 0xffff0000, v31
	v_fmac_f32_e32 v233, v193, v247
	v_fmac_f32_e32 v234, v193, v248
	v_lshlrev_b32_e32 v247, 16, v32
	v_and_b32_e32 v248, 0xffff0000, v32
	v_fmac_f32_e32 v227, v194, v247
	v_fmac_f32_e32 v228, v194, v248
	v_lshlrev_b32_e32 v247, 16, v33
	v_and_b32_e32 v248, 0xffff0000, v33
	v_fmac_f32_e32 v229, v194, v247
	v_fmac_f32_e32 v230, v194, v248
	v_lshlrev_b32_e32 v247, 16, v34
	v_and_b32_e32 v248, 0xffff0000, v34
	v_fmac_f32_e32 v231, v194, v247
	v_fmac_f32_e32 v232, v194, v248
	v_lshlrev_b32_e32 v247, 16, v35
	v_and_b32_e32 v248, 0xffff0000, v35
	v_fmac_f32_e32 v233, v194, v247
	v_fmac_f32_e32 v234, v194, v248
	s_cmp_lt_u32 s15, 8
	s_cbranch_scc1 .Lpl_acc_done
; __device__ __forceinline__ float bflo(unsigned w) { return __uint_as_float(w << 16); }
; __device__ __forceinline__ float bfhi(unsigned w) { return __uint_as_float(w & 0xffff0000u); }
; template <int W> __device__ __forceinline__ void pool_task(const bf16* __restrict__ z, const bf16* __restrict__ pwt, const float* __restrict__ pool_scale, bf16* __restrict__ y, int g, int r0, int lane) {
;     ...
;             for (int j = 0; j < CH; ++j) { const int lag = c0 + j, lg = lag < cnt ? lag : 0; u[j] = *(const v4u*)(zp - (size_t)lg * DIN); }
; #pragma unroll
;             for (int j = 0; j < CH; ++j) { const float wgt = (c0 + j) < cnt ? 1.0f : 0.0f;
; #pragma unroll
;                 for (int i = 0; i < 4; ++i) { sm[2 * i] += wgt * bflo(u[j][i]); sm[2 * i + 1] += wgt * bfhi(u[j][i]); } }
	v_lshlrev_b32_e32 v247, 16, v36
	v_and_b32_e32 v248, 0xffff0000, v36
	v_fmac_f32_e32 v227, v195, v247
	v_fmac_f32_e32 v228, v195, v248
	v_lshlrev_b32_e32 v247, 16, v37
	v_and_b32_e32 v248, 0xffff0000, v37
	v_fmac_f32_e32 v229, v195, v247
	v_fmac_f32_e32 v230, v195, v248
	v_lshlrev_b32_e32 v247, 16, v38
	v_and_b32_e32 v248, 0xffff0000, v38
	v_fmac_f32_e32 v231, v195, v247
	v_fmac_f32_e32 v232, v195, v248
	v_lshlrev_b32_e32 v247, 16, v39
	v_and_b32_e32 v248, 0xffff0000, v39
	v_fmac_f32_e32 v233, v195, v247
	v_fmac_f32_e32 v234, v195, v248
	v_lshlrev_b32_e32 v247, 16, v40
	v_and_b32_e32 v248, 0xffff0000, v40
	v_fmac_f32_e32 v227, v196, v247
	v_fmac_f32_e32 v228, v196, v248
	v_lshlrev_b32_e32 v247, 16, v41
	v_and_b32_e32 v248, 0xffff0000, v41
	v_fmac_f32_e32 v229, v196, v247
	v_fmac_f32_e32 v230, v196, v248
	v_lshlrev_b32_e32 v247, 16, v42
	v_and_b32_e32 v248, 0xffff0000, v42
	v_fmac_f32_e32 v231, v196, v247
	v_fmac_f32_e32 v232, v196, v248
	v_lshlrev_b32_e32 v247, 16, v43
	v_and_b32_e32 v248, 0xffff0000, v43
	v_fmac_f32_e32 v233, v196, v247
	v_fmac_f32_e32 v234, v196, v248
	v_lshlrev_b32_e32 v247, 16, v44
	v_and_b32_e32 v248, 0xffff0000, v44
	v_fmac_f32_e32 v227, v197, v247
	v_fmac_f32_e32 v228, v197, v248
	v_lshlrev_b32_e32 v247, 16, v45
	v_and_b32_e32 v248, 0xffff0000, v45
	v_fmac_f32_e32 v229, v197, v247
	v_fmac_f32_e32 v230, v197, v248
	v_lshlrev_b32_e32 v247, 16, v46
	v_and_b32_e32 v248, 0xffff0000, v46
	v_fmac_f32_e32 v231, v197, v247
	v_fmac_f32_e32 v232, v197, v248
	v_lshlrev_b32_e32 v247, 16, v47
	v_and_b32_e32 v248, 0xffff0000, v47
	v_fmac_f32_e32 v233, v197, v247
	v_fmac_f32_e32 v234, v197, v248
	v_lshlrev_b32_e32 v247, 16, v50
	v_and_b32_e32 v248, 0xffff0000, v50
	v_fmac_f32_e32 v227, v198, v247
	v_fmac_f32_e32 v228, v198, v248
	v_lshlrev_b32_e32 v247, 16, v51
	v_and_b32_e32 v248, 0xffff0000, v51
	v_fmac_f32_e32 v229, v198, v247
	v_fmac_f32_e32 v230, v198, v248
	v_lshlrev_b32_e32 v247, 16, v52
	v_and_b32_e32 v248, 0xffff0000, v52
	v_fmac_f32_e32 v231, v198, v247
	v_fmac_f32_e32 v232, v198, v248
	v_lshlrev_b32_e32 v247, 16, v53
	v_and_b32_e32 v248, 0xffff0000, v53
	v_fmac_f32_e32 v233, v198, v247
	v_fmac_f32_e32 v234, v198, v248
	v_lshlrev_b32_e32 v247, 16, v54
	v_and_b32_e32 v248, 0xffff0000, v54
	v_fmac_f32_e32 v227, v199, v247
	v_fmac_f32_e32 v228, v199, v248
	v_lshlrev_b32_e32 v247, 16, v55
	v_and_b32_e32 v248, 0xffff0000, v55
	v_fmac_f32_e32 v229, v199, v247
	v_fmac_f32_e32 v230, v199, v248
	v_lshlrev_b32_e32 v247, 16, v56
	v_and_b32_e32 v248, 0xffff0000, v56
	v_fmac_f32_e32 v231, v199, v247
	v_fmac_f32_e32 v232, v199, v248
	v_lshlrev_b32_e32 v247, 16, v57
	v_and_b32_e32 v248, 0xffff0000, v57
	v_fmac_f32_e32 v233, v199, v247
	v_fmac_f32_e32 v234, v199, v248
	v_lshlrev_b32_e32 v247, 16, v58
	v_and_b32_e32 v248, 0xffff0000, v58
	v_fmac_f32_e32 v227, v200, v247
	v_fmac_f32_e32 v228, v200, v248
	v_lshlrev_b32_e32 v247, 16, v59
	v_and_b32_e32 v248, 0xffff0000, v59
	v_fmac_f32_e32 v229, v200, v247
	v_fmac_f32_e32 v230, v200, v248
	v_lshlrev_b32_e32 v247, 16, v60
	v_and_b32_e32 v248, 0xffff0000, v60
	v_fmac_f32_e32 v231, v200, v247
	v_fmac_f32_e32 v232, v200, v248
	v_lshlrev_b32_e32 v247, 16, v61
	v_and_b32_e32 v248, 0xffff0000, v61
	v_fmac_f32_e32 v233, v200, v247
	v_fmac_f32_e32 v234, v200, v248
	v_lshlrev_b32_e32 v247, 16, v62
	v_and_b32_e32 v248, 0xffff0000, v62
	v_fmac_f32_e32 v227, v201, v247
	v_fmac_f32_e32 v228, v201, v248
	v_lshlrev_b32_e32 v247, 16, v63
	v_and_b32_e32 v248, 0xffff0000, v63
	v_fmac_f32_e32 v229, v201, v247
	v_fmac_f32_e32 v230, v201, v248
	v_lshlrev_b32_e32 v247, 16, v64
	v_and_b32_e32 v248, 0xffff0000, v64
	v_fmac_f32_e32 v231, v201, v247
	v_fmac_f32_e32 v232, v201, v248
	v_lshlrev_b32_e32 v247, 16, v65
	v_and_b32_e32 v248, 0xffff0000, v65
	v_fmac_f32_e32 v233, v201, v247
	v_fmac_f32_e32 v234, v201, v248
	v_lshlrev_b32_e32 v247, 16, v66
	v_and_b32_e32 v248, 0xffff0000, v66
	v_fmac_f32_e32 v227, v202, v247
	v_fmac_f32_e32 v228, v202, v248
	v_lshlrev_b32_e32 v247, 16, v67
	v_and_b32_e32 v248, 0xffff0000, v67
	v_fmac_f32_e32 v229, v202, v247
	v_fmac_f32_e32 v230, v202, v248
	v_lshlrev_b32_e32 v247, 16, v68
	v_and_b32_e32 v248, 0xffff0000, v68
	v_fmac_f32_e32 v231, v202, v247
	v_fmac_f32_e32 v232, v202, v248
	v_lshlrev_b32_e32 v247, 16, v69
	v_and_b32_e32 v248, 0xffff0000, v69
	v_fmac_f32_e32 v233, v202, v247
	v_fmac_f32_e32 v234, v202, v248
; __device__ __forceinline__ unsigned pk2(float lo, float hi) { return pg8::cvt_pk_bf16(lo, hi); }
; __device__ __forceinline__ float bflo(unsigned w) { return __uint_as_float(w << 16); }
; __device__ __forceinline__ float bfhi(unsigned w) { return __uint_as_float(w & 0xffff0000u); }
; template <int W> __device__ __forceinline__ void pool_task(const bf16* __restrict__ z, const bf16* __restrict__ pwt, const float* __restrict__ pool_scale, bf16* __restrict__ y, int g, int r0, int lane) {
;     ...
;         v4u pw;
; #pragma unroll
;         for (int i = 0; i < 4; ++i) pw[i] = pk2(sm[2 * i] * icnt - bflo(u0[i]), sm[2 * i + 1] * icnt - bfhi(u0[i]));
;         af[kc] = __builtin_bit_cast(bf16x8, pw); }
;     const bf16* wg = pwt + (size_t)g * 16384 + (size_t)fr * 128 + 8 * fq;
; #pragma unroll 1
;     for (int nh = 0; nh < 2; ++nh) {
;         bf16x8 wf[4][4]; f32x4 sc[4];
; #pragma unroll
;         for (int q = 0; q < 4; ++q) { const int nt = 4 * nh + q;
; #pragma unroll
;             for (int kc = 0; kc < 4; ++kc) wf[q][kc] = *(const bf16x8*)(wg + (size_t)nt * 16 * 128 + 32 * kc);
;             sc[q] = *(const f32x4*)(pool_scale + 128 * g + 16 * nt + 4 * fq); }
; #pragma unroll
;         for (int q = 0; q < 4; ++q) { const int nt = 4 * nh + q; f32x4 acc = (f32x4){0.f, 0.f, 0.f, 0.f};
; #pragma unroll
;             for (int kc = 0; kc < 4; ++kc) acc = __builtin_amdgcn_mfma_f32_16x16x32_bf16(wf[q][kc], af[kc], acc, 0, 0, 0);
;             const int dc = 128 * g + 16 * nt + 4 * fq;
;             v2u o; o.x = pk2(acc[0] * sc[q][0], acc[1] * sc[q][1]); o.y = pk2(acc[2] * sc[q][2], acc[3] * sc[q][3]);
;             *(v2u*)(y + (size_t)row * DM + 1536 + dc) = o; }
.Lpl_acc_done:
	v_fma_f32 v227, v245, v227, -v219
	v_fma_f32 v228, v245, v228, -v220
	v_fma_f32 v229, v245, v229, -v221
	v_fma_f32 v230, v245, v230, -v222
	v_fma_f32 v231, v245, v231, -v223
	v_fma_f32 v232, v245, v232, -v224
	v_fma_f32 v233, v245, v233, -v225
	v_fma_f32 v234, v245, v234, -v226
	v_cvt_pk_bf16_f32 v134, v227, v228
	v_cvt_pk_bf16_f32 v135, v229, v230
	v_cvt_pk_bf16_f32 v136, v231, v232
	v_cvt_pk_bf16_f32 v137, v233, v234
	s_waitcnt vmcnt(0)
	s_nop 1
	v_mfma_f32_16x16x32_bf16 v[102:105], v[70:73], v[134:137], v[102:105]
	v_mfma_f32_16x16x32_bf16 v[106:109], v[74:77], v[134:137], v[106:109]
	v_mfma_f32_16x16x32_bf16 v[110:113], v[78:81], v[134:137], v[110:113]
	v_mfma_f32_16x16x32_bf16 v[114:117], v[82:85], v[134:137], v[114:117]
	v_mfma_f32_16x16x32_bf16 v[118:121], v[86:89], v[134:137], v[118:121]
	v_mfma_f32_16x16x32_bf16 v[122:125], v[90:93], v[134:137], v[122:125]
	v_mfma_f32_16x16x32_bf16 v[126:129], v[94:97], v[134:137], v[126:129]
	v_mfma_f32_16x16x32_bf16 v[130:133], v[98:101], v[134:137], v[130:133]
	s_add_u32 s0, s0, 64
	s_addc_u32 s1, s1, 0
	s_add_u32 s6, s6, 64
	s_addc_u32 s7, s7, 0
	s_add_i32 s13, s13, 1
	s_cmp_lt_u32 s13, 4
	s_cbranch_scc1 .Lpl_kc
	global_load_dwordx4 v[4:7], v244, s[8:9]
	global_load_dwordx4 v[8:11], v244, s[8:9] offset:64
	global_load_dwordx4 v[12:15], v244, s[8:9] offset:128
	global_load_dwordx4 v[16:19], v244, s[8:9] offset:192
	global_load_dwordx4 v[20:23], v244, s[8:9] offset:256
	global_load_dwordx4 v[24:27], v244, s[8:9] offset:320
	global_load_dwordx4 v[28:31], v244, s[8:9] offset:384
	global_load_dwordx4 v[32:35], v244, s[8:9] offset:448
	s_nop 7
	s_waitcnt vmcnt(7)
	v_mul_f32_e32 v247, v102, v4
	v_mul_f32_e32 v248, v103, v5
	v_mul_f32_e32 v249, v104, v6
	v_mul_f32_e32 v250, v105, v7
	v_cvt_pk_bf16_f32 v184, v247, v248
	v_cvt_pk_bf16_f32 v185, v249, v250
	global_store_dwordx2 v243, v[184:185], s[10:11]
	s_waitcnt vmcnt(6)
	v_mul_f32_e32 v247, v106, v8
	v_mul_f32_e32 v248, v107, v9
	v_mul_f32_e32 v249, v108, v10
	v_mul_f32_e32 v250, v109, v11
	v_cvt_pk_bf16_f32 v186, v247, v248
	v_cvt_pk_bf16_f32 v187, v249, v250
	global_store_dwordx2 v243, v[186:187], s[10:11] offset:32
	s_waitcnt vmcnt(5)
	v_mul_f32_e32 v247, v110, v12
	v_mul_f32_e32 v248, v111, v13
	v_mul_f32_e32 v249, v112, v14
	v_mul_f32_e32 v250, v113, v15
	v_cvt_pk_bf16_f32 v184, v247, v248
	v_cvt_pk_bf16_f32 v185, v249, v250
	global_store_dwordx2 v243, v[184:185], s[10:11] offset:64
	s_waitcnt vmcnt(4)
	v_mul_f32_e32 v247, v114, v16
	v_mul_f32_e32 v248, v115, v17
	v_mul_f32_e32 v249, v116, v18
	v_mul_f32_e32 v250, v117, v19
	v_cvt_pk_bf16_f32 v186, v247, v248
	v_cvt_pk_bf16_f32 v187, v249, v250
	global_store_dwordx2 v243, v[186:187], s[10:11] offset:96
	s_waitcnt vmcnt(3)
	v_mul_f32_e32 v247, v118, v20
	v_mul_f32_e32 v248, v119, v21
	v_mul_f32_e32 v249, v120, v22
	v_mul_f32_e32 v250, v121, v23
	v_cvt_pk_bf16_f32 v184, v247, v248
	v_cvt_pk_bf16_f32 v185, v249, v250
	global_store_dwordx2 v243, v[184:185], s[10:11] offset:128
	s_waitcnt vmcnt(2)
	v_mul_f32_e32 v247, v122, v24
	v_mul_f32_e32 v248, v123, v25
	v_mul_f32_e32 v249, v124, v26
	v_mul_f32_e32 v250, v125, v27
	v_cvt_pk_bf16_f32 v186, v247, v248
	v_cvt_pk_bf16_f32 v187, v249, v250
	global_store_dwordx2 v243, v[186:187], s[10:11] offset:160
	s_waitcnt vmcnt(1)
	v_mul_f32_e32 v247, v126, v28
	v_mul_f32_e32 v248, v127, v29
	v_mul_f32_e32 v249, v128, v30
	v_mul_f32_e32 v250, v129, v31
	v_cvt_pk_bf16_f32 v184, v247, v248
	v_cvt_pk_bf16_f32 v185, v249, v250
	global_store_dwordx2 v243, v[184:185], s[10:11] offset:192
	s_waitcnt vmcnt(0)
	v_mul_f32_e32 v247, v130, v32
	v_mul_f32_e32 v248, v131, v33
	v_mul_f32_e32 v249, v132, v34
	v_mul_f32_e32 v250, v133, v35
	v_cvt_pk_bf16_f32 v186, v247, v248
	v_cvt_pk_bf16_f32 v187, v249, v250
	global_store_dwordx2 v243, v[186:187], s[10:11] offset:224
	s_branch .LBB0_393
